# P6 EpiRes and P8 EpiDown epilogues hand-written: x2 stays in accumulator registers through the row-statistics exchange (no store/reload), x loads issued ahead, bf16 x1*G2 stored 16 B per lane
# speedup vs baseline: 1.0268x; 1.0154x over previous
.LBB0_1293:
	s_sext_i32_i8 s4, s26
	s_lshl_b32 s35, s4, 8
	s_lshl_b32 s38, s78, 8
	s_cmp_gt_i32 s79, 0
	s_cbranch_scc0 .Lp6_noq
	s_sub_i32 s16, s79, 1
	s_and_b32 s39, s16, 1
	s_lshl_b32 s39, s39, 7
	s_add_i32 s35, s35, s39
	s_lshr_b32 s16, s16, 1
	s_lshl_b32 s16, s16, 7
	s_add_i32 s38, s38, s16
.Lp6_noq:
	s_sub_i32 s16, s78, 32
	s_lshr_b32 s16, s16, 2
	s_add_i32 s16, s16, 1
	s_cmp_gt_i32 s78, 31
	s_cselect_b32 s34, s16, 0
	v_readlane_b32 s80, v253, 22
	v_readlane_b32 s81, v253, 23
	v_readlane_b32 s82, v253, 26
	v_readlane_b32 s83, v253, 27
	v_readlane_b32 s84, v253, 28
	v_readlane_b32 s85, v253, 29
	v_readlane_b32 s94, v253, 20
	v_readlane_b32 s95, v253, 21
	s_mul_i32 s16, s34, 0xc000
	s_addk_i32 s16, 0x4000
	s_add_u32 s80, s80, s16
	s_addc_u32 s81, s81, 0
	s_lshl_b32 s16, s34, 13
	s_add_u32 s46, s59, s16
	s_addc_u32 s47, s60, 0
	s_cmp_lt_i32 s78, 32
	s_cbranch_scc1 .Lp6_prompt
	s_add_u32 s82, s84, 0xfc000000
	s_addc_u32 s83, s85, -1
.Lp6_prompt:
	v_add_u32_e32 v3, s35, v245
	v_lshlrev_b32_e32 v251, 2, v3
	global_load_dwordx4 v[68:71], v251, s[80:81]
	global_load_dwordx4 v[72:75], v251, s[80:81] offset:64
	global_load_dwordx4 v[76:79], v251, s[80:81] offset:512
	global_load_dwordx4 v[80:83], v251, s[80:81] offset:576
	global_load_dwordx4 v[92:95], v251, s[46:47]
	global_load_dwordx4 v[96:99], v251, s[46:47] offset:64
	global_load_dwordx4 v[100:103], v251, s[46:47] offset:512
	global_load_dwordx4 v[84:87], v251, s[46:47] offset:576
	v_add_u32_e32 v1, s38, v244
	v_lshlrev_b32_e32 v251, 2, v1
	v_lshl_add_u32 v1, v1, 11, v3
	v_bfe_u32 v3, v245, 2, 1
	v_mul_u32_u24_e32 v3, 24, v3
	v_lshl_add_u32 v240, v1, 1, v3
	v_lshlrev_b32_e32 v1, 2, v1
	s_cmp_gt_i32 s79, 0
	s_cbranch_scc1 .Lp6_quart
	v_mov_b32_e32 v236, v1
	global_load_dwordx4 v[164:167], v236, s[82:83] offset:0 nt
	global_load_dwordx4 v[168:171], v236, s[82:83] offset:64 nt
	global_load_dwordx4 v[172:175], v236, s[82:83] offset:512 nt
	global_load_dwordx4 v[176:179], v236, s[82:83] offset:576 nt
	v_add_u32_e32 v237, 0x20000, v1
	global_load_dwordx4 v[180:183], v237, s[82:83] offset:0 nt
	global_load_dwordx4 v[184:187], v237, s[82:83] offset:64 nt
	global_load_dwordx4 v[188:191], v237, s[82:83] offset:512 nt
	global_load_dwordx4 v[192:195], v237, s[82:83] offset:576 nt
	v_add_u32_e32 v236, 0x40000, v1
	global_load_dwordx4 v[196:199], v236, s[82:83] offset:0 nt
	global_load_dwordx4 v[200:203], v236, s[82:83] offset:64 nt
	global_load_dwordx4 v[204:207], v236, s[82:83] offset:512 nt
	global_load_dwordx4 v[208:211], v236, s[82:83] offset:576 nt
	v_add_u32_e32 v237, 0x60000, v1
	global_load_dwordx4 v[212:215], v237, s[82:83] offset:0 nt
	s_waitcnt vmcnt(12)
	v_mov_b32_e32 v238, v1
	v_mov_b32_e32 v239, v240
	v_pk_fma_f32 v[160:161], v[160:161], v[68:69], v[164:165]
	v_pk_fma_f32 v[162:163], v[162:163], v[70:71], v[166:167]
	global_store_dwordx4 v238, v[160:163], s[94:95] offset:0
	v_pk_mul_f32 v[2:3], v[160:161], v[160:161]
	v_pk_fma_f32 v[2:3], v[162:163], v[162:163], v[2:3]
	v_pk_mul_f32 v[164:165], v[160:161], v[92:93]
	v_pk_mul_f32 v[166:167], v[162:163], v[94:95]
	v_cvt_pk_bf16_f32 v216, v164, v165
	v_cvt_pk_bf16_f32 v217, v166, v167
	global_load_dwordx4 v[164:167], v237, s[82:83] offset:64 nt
	s_waitcnt vmcnt(13)
	v_pk_fma_f32 v[156:157], v[156:157], v[72:73], v[168:169]
	v_pk_fma_f32 v[158:159], v[158:159], v[74:75], v[170:171]
	global_store_dwordx4 v238, v[156:159], s[94:95] offset:64
	v_pk_fma_f32 v[2:3], v[156:157], v[156:157], v[2:3]
	v_pk_fma_f32 v[2:3], v[158:159], v[158:159], v[2:3]
	v_pk_mul_f32 v[168:169], v[156:157], v[96:97]
	v_pk_mul_f32 v[170:171], v[158:159], v[98:99]
	v_cvt_pk_bf16_f32 v218, v168, v169
	v_cvt_pk_bf16_f32 v219, v170, v171
	s_nop 1
	v_permlane16_swap_b32 v216, v218
	v_permlane16_swap_b32 v217, v219
	global_store_dwordx4 v239, v[216:219], s[10:11] offset:0
	global_load_dwordx4 v[168:171], v237, s[82:83] offset:512 nt
	s_waitcnt vmcnt(15)
	v_pk_fma_f32 v[144:145], v[144:145], v[76:77], v[172:173]
	v_pk_fma_f32 v[146:147], v[146:147], v[78:79], v[174:175]
	global_store_dwordx4 v238, v[144:147], s[94:95] offset:512
	v_pk_fma_f32 v[2:3], v[144:145], v[144:145], v[2:3]
	v_pk_fma_f32 v[2:3], v[146:147], v[146:147], v[2:3]
	v_pk_mul_f32 v[172:173], v[144:145], v[100:101]
	v_pk_mul_f32 v[174:175], v[146:147], v[102:103]
	v_cvt_pk_bf16_f32 v220, v172, v173
	v_cvt_pk_bf16_f32 v221, v174, v175
	global_load_dwordx4 v[172:175], v237, s[82:83] offset:576 nt
	s_waitcnt vmcnt(16)
	v_pk_fma_f32 v[140:141], v[140:141], v[80:81], v[176:177]
	v_pk_fma_f32 v[142:143], v[142:143], v[82:83], v[178:179]
	global_store_dwordx4 v238, v[140:143], s[94:95] offset:576
	v_pk_fma_f32 v[2:3], v[140:141], v[140:141], v[2:3]
	v_pk_fma_f32 v[2:3], v[142:143], v[142:143], v[2:3]
	v_pk_mul_f32 v[176:177], v[140:141], v[84:85]
	v_pk_mul_f32 v[178:179], v[142:143], v[86:87]
	v_cvt_pk_bf16_f32 v222, v176, v177
	v_cvt_pk_bf16_f32 v223, v178, v179
	s_nop 1
	v_permlane16_swap_b32 v220, v222
	v_permlane16_swap_b32 v221, v223
	global_store_dwordx4 v239, v[220:223], s[10:11] offset:256
	v_add_f32_e32 v160, v2, v3
	v_add_u32_e32 v236, 0x100000, v1
	global_load_dwordx4 v[176:179], v236, s[82:83] offset:0 nt
	s_waitcnt vmcnt(18)
	v_add_u32_e32 v238, 0x20000, v1
	v_add_u32_e32 v239, 0x10000, v240
	v_pk_fma_f32 v[152:153], v[152:153], v[68:69], v[180:181]
	v_pk_fma_f32 v[154:155], v[154:155], v[70:71], v[182:183]
	global_store_dwordx4 v238, v[152:155], s[94:95] offset:0
	v_pk_mul_f32 v[2:3], v[152:153], v[152:153]
	v_pk_fma_f32 v[2:3], v[154:155], v[154:155], v[2:3]
	v_pk_mul_f32 v[180:181], v[152:153], v[92:93]
	v_pk_mul_f32 v[182:183], v[154:155], v[94:95]
	v_cvt_pk_bf16_f32 v224, v180, v181
	v_cvt_pk_bf16_f32 v225, v182, v183
	global_load_dwordx4 v[180:183], v236, s[82:83] offset:64 nt
	s_waitcnt vmcnt(19)
	v_pk_fma_f32 v[148:149], v[148:149], v[72:73], v[184:185]
	v_pk_fma_f32 v[150:151], v[150:151], v[74:75], v[186:187]
	global_store_dwordx4 v238, v[148:151], s[94:95] offset:64
	v_pk_fma_f32 v[2:3], v[148:149], v[148:149], v[2:3]
	v_pk_fma_f32 v[2:3], v[150:151], v[150:151], v[2:3]
	v_pk_mul_f32 v[184:185], v[148:149], v[96:97]
	v_pk_mul_f32 v[186:187], v[150:151], v[98:99]
	v_cvt_pk_bf16_f32 v226, v184, v185
	v_cvt_pk_bf16_f32 v227, v186, v187
	s_nop 1
	v_permlane16_swap_b32 v224, v226
	v_permlane16_swap_b32 v225, v227
	global_store_dwordx4 v239, v[224:227], s[10:11] offset:0
	global_load_dwordx4 v[184:187], v236, s[82:83] offset:512 nt
	s_waitcnt vmcnt(21)
	v_pk_fma_f32 v[128:129], v[128:129], v[76:77], v[188:189]
	v_pk_fma_f32 v[130:131], v[130:131], v[78:79], v[190:191]
	global_store_dwordx4 v238, v[128:131], s[94:95] offset:512
	v_pk_fma_f32 v[2:3], v[128:129], v[128:129], v[2:3]
	v_pk_fma_f32 v[2:3], v[130:131], v[130:131], v[2:3]
	v_pk_mul_f32 v[188:189], v[128:129], v[100:101]
	v_pk_mul_f32 v[190:191], v[130:131], v[102:103]
	v_cvt_pk_bf16_f32 v216, v188, v189
	v_cvt_pk_bf16_f32 v217, v190, v191
	global_load_dwordx4 v[188:191], v236, s[82:83] offset:576 nt
	s_waitcnt vmcnt(22)
	v_pk_fma_f32 v[124:125], v[124:125], v[80:81], v[192:193]
	v_pk_fma_f32 v[126:127], v[126:127], v[82:83], v[194:195]
	global_store_dwordx4 v238, v[124:127], s[94:95] offset:576
	v_pk_fma_f32 v[2:3], v[124:125], v[124:125], v[2:3]
	v_pk_fma_f32 v[2:3], v[126:127], v[126:127], v[2:3]
	v_pk_mul_f32 v[192:193], v[124:125], v[84:85]
	v_pk_mul_f32 v[194:195], v[126:127], v[86:87]
	v_cvt_pk_bf16_f32 v218, v192, v193
	v_cvt_pk_bf16_f32 v219, v194, v195
	s_nop 1
	v_permlane16_swap_b32 v216, v218
	v_permlane16_swap_b32 v217, v219
	global_store_dwordx4 v239, v[216:219], s[10:11] offset:256
	v_add_f32_e32 v152, v2, v3
	v_add_u32_e32 v237, 0x120000, v1
	global_load_dwordx4 v[192:195], v237, s[82:83] offset:0 nt
	s_waitcnt vmcnt(24)
	v_add_u32_e32 v238, 0x40000, v1
	v_add_u32_e32 v239, 0x20000, v240
	v_pk_fma_f32 v[136:137], v[136:137], v[68:69], v[196:197]
	v_pk_fma_f32 v[138:139], v[138:139], v[70:71], v[198:199]
	global_store_dwordx4 v238, v[136:139], s[94:95] offset:0
	v_pk_mul_f32 v[2:3], v[136:137], v[136:137]
	v_pk_fma_f32 v[2:3], v[138:139], v[138:139], v[2:3]
	v_pk_mul_f32 v[196:197], v[136:137], v[92:93]
	v_pk_mul_f32 v[198:199], v[138:139], v[94:95]
	v_cvt_pk_bf16_f32 v220, v196, v197
	v_cvt_pk_bf16_f32 v221, v198, v199
	global_load_dwordx4 v[196:199], v237, s[82:83] offset:64 nt
	s_waitcnt vmcnt(25)
	v_pk_fma_f32 v[132:133], v[132:133], v[72:73], v[200:201]
	v_pk_fma_f32 v[134:135], v[134:135], v[74:75], v[202:203]
	global_store_dwordx4 v238, v[132:135], s[94:95] offset:64
	v_pk_fma_f32 v[2:3], v[132:133], v[132:133], v[2:3]
	v_pk_fma_f32 v[2:3], v[134:135], v[134:135], v[2:3]
	v_pk_mul_f32 v[200:201], v[132:133], v[96:97]
	v_pk_mul_f32 v[202:203], v[134:135], v[98:99]
	v_cvt_pk_bf16_f32 v222, v200, v201
	v_cvt_pk_bf16_f32 v223, v202, v203
	s_nop 1
	v_permlane16_swap_b32 v220, v222
	v_permlane16_swap_b32 v221, v223
	global_store_dwordx4 v239, v[220:223], s[10:11] offset:0
	global_load_dwordx4 v[200:203], v237, s[82:83] offset:512 nt
	s_waitcnt vmcnt(27)
	v_pk_fma_f32 v[116:117], v[116:117], v[76:77], v[204:205]
	v_pk_fma_f32 v[118:119], v[118:119], v[78:79], v[206:207]
	global_store_dwordx4 v238, v[116:119], s[94:95] offset:512
	v_pk_fma_f32 v[2:3], v[116:117], v[116:117], v[2:3]
	v_pk_fma_f32 v[2:3], v[118:119], v[118:119], v[2:3]
	v_pk_mul_f32 v[204:205], v[116:117], v[100:101]
	v_pk_mul_f32 v[206:207], v[118:119], v[102:103]
	v_cvt_pk_bf16_f32 v224, v204, v205
	v_cvt_pk_bf16_f32 v225, v206, v207
	global_load_dwordx4 v[204:207], v237, s[82:83] offset:576 nt
	s_waitcnt vmcnt(28)
	v_pk_fma_f32 v[108:109], v[108:109], v[80:81], v[208:209]
	v_pk_fma_f32 v[110:111], v[110:111], v[82:83], v[210:211]
	global_store_dwordx4 v238, v[108:111], s[94:95] offset:576
	v_pk_fma_f32 v[2:3], v[108:109], v[108:109], v[2:3]
	v_pk_fma_f32 v[2:3], v[110:111], v[110:111], v[2:3]
	v_pk_mul_f32 v[208:209], v[108:109], v[84:85]
	v_pk_mul_f32 v[210:211], v[110:111], v[86:87]
	v_cvt_pk_bf16_f32 v226, v208, v209
	v_cvt_pk_bf16_f32 v227, v210, v211
	s_nop 1
	v_permlane16_swap_b32 v224, v226
	v_permlane16_swap_b32 v225, v227
	global_store_dwordx4 v239, v[224:227], s[10:11] offset:256
	v_add_f32_e32 v136, v2, v3
	v_add_u32_e32 v236, 0x140000, v1
	global_load_dwordx4 v[208:211], v236, s[82:83] offset:0 nt
	s_waitcnt vmcnt(30)
	v_add_u32_e32 v238, 0x60000, v1
	v_add_u32_e32 v239, 0x30000, v240
	v_pk_fma_f32 v[120:121], v[120:121], v[68:69], v[212:213]
	v_pk_fma_f32 v[122:123], v[122:123], v[70:71], v[214:215]
	global_store_dwordx4 v238, v[120:123], s[94:95] offset:0
	v_pk_mul_f32 v[2:3], v[120:121], v[120:121]
	v_pk_fma_f32 v[2:3], v[122:123], v[122:123], v[2:3]
	v_pk_mul_f32 v[212:213], v[120:121], v[92:93]
	v_pk_mul_f32 v[214:215], v[122:123], v[94:95]
	v_cvt_pk_bf16_f32 v216, v212, v213
	v_cvt_pk_bf16_f32 v217, v214, v215
	global_load_dwordx4 v[212:215], v236, s[82:83] offset:64 nt
	s_waitcnt vmcnt(30)
	v_pk_fma_f32 v[112:113], v[112:113], v[72:73], v[164:165]
	v_pk_fma_f32 v[114:115], v[114:115], v[74:75], v[166:167]
	global_store_dwordx4 v238, v[112:115], s[94:95] offset:64
	v_pk_fma_f32 v[2:3], v[112:113], v[112:113], v[2:3]
	v_pk_fma_f32 v[2:3], v[114:115], v[114:115], v[2:3]
	v_pk_mul_f32 v[164:165], v[112:113], v[96:97]
	v_pk_mul_f32 v[166:167], v[114:115], v[98:99]
	v_cvt_pk_bf16_f32 v218, v164, v165
	v_cvt_pk_bf16_f32 v219, v166, v167
	s_nop 1
	v_permlane16_swap_b32 v216, v218
	v_permlane16_swap_b32 v217, v219
	global_store_dwordx4 v239, v[216:219], s[10:11] offset:0
	global_load_dwordx4 v[164:167], v236, s[82:83] offset:512 nt
	s_waitcnt vmcnt(30)
	v_pk_fma_f32 v[104:105], v[104:105], v[76:77], v[168:169]
	v_pk_fma_f32 v[106:107], v[106:107], v[78:79], v[170:171]
	global_store_dwordx4 v238, v[104:107], s[94:95] offset:512
	v_pk_fma_f32 v[2:3], v[104:105], v[104:105], v[2:3]
	v_pk_fma_f32 v[2:3], v[106:107], v[106:107], v[2:3]
	v_pk_mul_f32 v[168:169], v[104:105], v[100:101]
	v_pk_mul_f32 v[170:171], v[106:107], v[102:103]
	v_cvt_pk_bf16_f32 v220, v168, v169
	v_cvt_pk_bf16_f32 v221, v170, v171
	global_load_dwordx4 v[168:171], v236, s[82:83] offset:576 nt
	s_waitcnt vmcnt(30)
	v_pk_fma_f32 v[88:89], v[88:89], v[80:81], v[172:173]
	v_pk_fma_f32 v[90:91], v[90:91], v[82:83], v[174:175]
	global_store_dwordx4 v238, v[88:91], s[94:95] offset:576
	v_pk_fma_f32 v[2:3], v[88:89], v[88:89], v[2:3]
	v_pk_fma_f32 v[2:3], v[90:91], v[90:91], v[2:3]
	v_pk_mul_f32 v[172:173], v[88:89], v[84:85]
	v_pk_mul_f32 v[174:175], v[90:91], v[86:87]
	v_cvt_pk_bf16_f32 v222, v172, v173
	v_cvt_pk_bf16_f32 v223, v174, v175
	s_nop 1
	v_permlane16_swap_b32 v220, v222
	v_permlane16_swap_b32 v221, v223
	global_store_dwordx4 v239, v[220:223], s[10:11] offset:256
	v_add_f32_e32 v120, v2, v3
	v_add_u32_e32 v237, 0x160000, v1
	global_load_dwordx4 v[172:175], v237, s[82:83] offset:0 nt
	s_waitcnt vmcnt(30)
	v_add_u32_e32 v238, 0x100000, v1
	v_add_u32_e32 v239, 0x80000, v240
	v_pk_fma_f32 v[64:65], v[64:65], v[68:69], v[176:177]
	v_pk_fma_f32 v[66:67], v[66:67], v[70:71], v[178:179]
	global_store_dwordx4 v238, v[64:67], s[94:95] offset:0
	v_pk_mul_f32 v[2:3], v[64:65], v[64:65]
	v_pk_fma_f32 v[2:3], v[66:67], v[66:67], v[2:3]
	v_pk_mul_f32 v[176:177], v[64:65], v[92:93]
	v_pk_mul_f32 v[178:179], v[66:67], v[94:95]
	v_cvt_pk_bf16_f32 v224, v176, v177
	v_cvt_pk_bf16_f32 v225, v178, v179
	global_load_dwordx4 v[176:179], v237, s[82:83] offset:64 nt
	s_waitcnt vmcnt(30)
	v_pk_fma_f32 v[60:61], v[60:61], v[72:73], v[180:181]
	v_pk_fma_f32 v[62:63], v[62:63], v[74:75], v[182:183]
	global_store_dwordx4 v238, v[60:63], s[94:95] offset:64
	v_pk_fma_f32 v[2:3], v[60:61], v[60:61], v[2:3]
	v_pk_fma_f32 v[2:3], v[62:63], v[62:63], v[2:3]
	v_pk_mul_f32 v[180:181], v[60:61], v[96:97]
	v_pk_mul_f32 v[182:183], v[62:63], v[98:99]
	v_cvt_pk_bf16_f32 v226, v180, v181
	v_cvt_pk_bf16_f32 v227, v182, v183
	s_nop 1
	v_permlane16_swap_b32 v224, v226
	v_permlane16_swap_b32 v225, v227
	global_store_dwordx4 v239, v[224:227], s[10:11] offset:0
	global_load_dwordx4 v[180:183], v237, s[82:83] offset:512 nt
	s_waitcnt vmcnt(30)
	v_pk_fma_f32 v[56:57], v[56:57], v[76:77], v[184:185]
	v_pk_fma_f32 v[58:59], v[58:59], v[78:79], v[186:187]
	global_store_dwordx4 v238, v[56:59], s[94:95] offset:512
	v_pk_fma_f32 v[2:3], v[56:57], v[56:57], v[2:3]
	v_pk_fma_f32 v[2:3], v[58:59], v[58:59], v[2:3]
	v_pk_mul_f32 v[184:185], v[56:57], v[100:101]
	v_pk_mul_f32 v[186:187], v[58:59], v[102:103]
	v_cvt_pk_bf16_f32 v216, v184, v185
	v_cvt_pk_bf16_f32 v217, v186, v187
	global_load_dwordx4 v[184:187], v237, s[82:83] offset:576 nt
	s_waitcnt vmcnt(30)
	v_pk_fma_f32 v[52:53], v[52:53], v[80:81], v[188:189]
	v_pk_fma_f32 v[54:55], v[54:55], v[82:83], v[190:191]
	global_store_dwordx4 v238, v[52:55], s[94:95] offset:576
	v_pk_fma_f32 v[2:3], v[52:53], v[52:53], v[2:3]
	v_pk_fma_f32 v[2:3], v[54:55], v[54:55], v[2:3]
	v_pk_mul_f32 v[188:189], v[52:53], v[84:85]
	v_pk_mul_f32 v[190:191], v[54:55], v[86:87]
	v_cvt_pk_bf16_f32 v218, v188, v189
	v_cvt_pk_bf16_f32 v219, v190, v191
	s_nop 1
	v_permlane16_swap_b32 v216, v218
	v_permlane16_swap_b32 v217, v219
	global_store_dwordx4 v239, v[216:219], s[10:11] offset:256
	v_add_f32_e32 v64, v2, v3
	s_waitcnt vmcnt(29)
	v_add_u32_e32 v238, 0x120000, v1
	v_add_u32_e32 v239, 0x90000, v240
	v_pk_fma_f32 v[48:49], v[48:49], v[68:69], v[192:193]
	v_pk_fma_f32 v[50:51], v[50:51], v[70:71], v[194:195]
	global_store_dwordx4 v238, v[48:51], s[94:95] offset:0
	v_pk_mul_f32 v[2:3], v[48:49], v[48:49]
	v_pk_fma_f32 v[2:3], v[50:51], v[50:51], v[2:3]
	v_pk_mul_f32 v[192:193], v[48:49], v[92:93]
	v_pk_mul_f32 v[194:195], v[50:51], v[94:95]
	v_cvt_pk_bf16_f32 v220, v192, v193
	v_cvt_pk_bf16_f32 v221, v194, v195
	s_waitcnt vmcnt(28)
	v_pk_fma_f32 v[44:45], v[44:45], v[72:73], v[196:197]
	v_pk_fma_f32 v[46:47], v[46:47], v[74:75], v[198:199]
	global_store_dwordx4 v238, v[44:47], s[94:95] offset:64
	v_pk_fma_f32 v[2:3], v[44:45], v[44:45], v[2:3]
	v_pk_fma_f32 v[2:3], v[46:47], v[46:47], v[2:3]
	v_pk_mul_f32 v[196:197], v[44:45], v[96:97]
	v_pk_mul_f32 v[198:199], v[46:47], v[98:99]
	v_cvt_pk_bf16_f32 v222, v196, v197
	v_cvt_pk_bf16_f32 v223, v198, v199
	s_nop 1
	v_permlane16_swap_b32 v220, v222
	v_permlane16_swap_b32 v221, v223
	global_store_dwordx4 v239, v[220:223], s[10:11] offset:0
	s_waitcnt vmcnt(27)
	v_pk_fma_f32 v[40:41], v[40:41], v[76:77], v[200:201]
	v_pk_fma_f32 v[42:43], v[42:43], v[78:79], v[202:203]
	global_store_dwordx4 v238, v[40:43], s[94:95] offset:512
	v_pk_fma_f32 v[2:3], v[40:41], v[40:41], v[2:3]
	v_pk_fma_f32 v[2:3], v[42:43], v[42:43], v[2:3]
	v_pk_mul_f32 v[200:201], v[40:41], v[100:101]
	v_pk_mul_f32 v[202:203], v[42:43], v[102:103]
	v_cvt_pk_bf16_f32 v224, v200, v201
	v_cvt_pk_bf16_f32 v225, v202, v203
	s_waitcnt vmcnt(26)
	v_pk_fma_f32 v[36:37], v[36:37], v[80:81], v[204:205]
	v_pk_fma_f32 v[38:39], v[38:39], v[82:83], v[206:207]
	global_store_dwordx4 v238, v[36:39], s[94:95] offset:576
	v_pk_fma_f32 v[2:3], v[36:37], v[36:37], v[2:3]
	v_pk_fma_f32 v[2:3], v[38:39], v[38:39], v[2:3]
	v_pk_mul_f32 v[204:205], v[36:37], v[84:85]
	v_pk_mul_f32 v[206:207], v[38:39], v[86:87]
	v_cvt_pk_bf16_f32 v226, v204, v205
	v_cvt_pk_bf16_f32 v227, v206, v207
	s_nop 1
	v_permlane16_swap_b32 v224, v226
	v_permlane16_swap_b32 v225, v227
	global_store_dwordx4 v239, v[224:227], s[10:11] offset:256
	v_add_f32_e32 v48, v2, v3
	s_waitcnt vmcnt(25)
	v_add_u32_e32 v238, 0x140000, v1
	v_add_u32_e32 v239, 0xa0000, v240
	v_pk_fma_f32 v[32:33], v[32:33], v[68:69], v[208:209]
	v_pk_fma_f32 v[34:35], v[34:35], v[70:71], v[210:211]
	global_store_dwordx4 v238, v[32:35], s[94:95] offset:0
	v_pk_mul_f32 v[2:3], v[32:33], v[32:33]
	v_pk_fma_f32 v[2:3], v[34:35], v[34:35], v[2:3]
	v_pk_mul_f32 v[208:209], v[32:33], v[92:93]
	v_pk_mul_f32 v[210:211], v[34:35], v[94:95]
	v_cvt_pk_bf16_f32 v216, v208, v209
	v_cvt_pk_bf16_f32 v217, v210, v211
	s_waitcnt vmcnt(24)
	v_pk_fma_f32 v[28:29], v[28:29], v[72:73], v[212:213]
	v_pk_fma_f32 v[30:31], v[30:31], v[74:75], v[214:215]
	global_store_dwordx4 v238, v[28:31], s[94:95] offset:64
	v_pk_fma_f32 v[2:3], v[28:29], v[28:29], v[2:3]
	v_pk_fma_f32 v[2:3], v[30:31], v[30:31], v[2:3]
	v_pk_mul_f32 v[212:213], v[28:29], v[96:97]
	v_pk_mul_f32 v[214:215], v[30:31], v[98:99]
	v_cvt_pk_bf16_f32 v218, v212, v213
	v_cvt_pk_bf16_f32 v219, v214, v215
	s_nop 1
	v_permlane16_swap_b32 v216, v218
	v_permlane16_swap_b32 v217, v219
	global_store_dwordx4 v239, v[216:219], s[10:11] offset:0
	s_waitcnt vmcnt(23)
	v_pk_fma_f32 v[24:25], v[24:25], v[76:77], v[164:165]
	v_pk_fma_f32 v[26:27], v[26:27], v[78:79], v[166:167]
	global_store_dwordx4 v238, v[24:27], s[94:95] offset:512
	v_pk_fma_f32 v[2:3], v[24:25], v[24:25], v[2:3]
	v_pk_fma_f32 v[2:3], v[26:27], v[26:27], v[2:3]
	v_pk_mul_f32 v[164:165], v[24:25], v[100:101]
	v_pk_mul_f32 v[166:167], v[26:27], v[102:103]
	v_cvt_pk_bf16_f32 v220, v164, v165
	v_cvt_pk_bf16_f32 v221, v166, v167
	s_waitcnt vmcnt(22)
	v_pk_fma_f32 v[20:21], v[20:21], v[80:81], v[168:169]
	v_pk_fma_f32 v[22:23], v[22:23], v[82:83], v[170:171]
	global_store_dwordx4 v238, v[20:23], s[94:95] offset:576
	v_pk_fma_f32 v[2:3], v[20:21], v[20:21], v[2:3]
	v_pk_fma_f32 v[2:3], v[22:23], v[22:23], v[2:3]
	v_pk_mul_f32 v[168:169], v[20:21], v[84:85]
	v_pk_mul_f32 v[170:171], v[22:23], v[86:87]
	v_cvt_pk_bf16_f32 v222, v168, v169
	v_cvt_pk_bf16_f32 v223, v170, v171
	s_nop 1
	v_permlane16_swap_b32 v220, v222
	v_permlane16_swap_b32 v221, v223
	global_store_dwordx4 v239, v[220:223], s[10:11] offset:256
	v_add_f32_e32 v32, v2, v3
	s_waitcnt vmcnt(21)
	v_add_u32_e32 v238, 0x160000, v1
	v_add_u32_e32 v239, 0xb0000, v240
	v_pk_fma_f32 v[16:17], v[16:17], v[68:69], v[172:173]
	v_pk_fma_f32 v[18:19], v[18:19], v[70:71], v[174:175]
	global_store_dwordx4 v238, v[16:19], s[94:95] offset:0
	v_pk_mul_f32 v[2:3], v[16:17], v[16:17]
	v_pk_fma_f32 v[2:3], v[18:19], v[18:19], v[2:3]
	v_pk_mul_f32 v[172:173], v[16:17], v[92:93]
	v_pk_mul_f32 v[174:175], v[18:19], v[94:95]
	v_cvt_pk_bf16_f32 v224, v172, v173
	v_cvt_pk_bf16_f32 v225, v174, v175
	s_waitcnt vmcnt(20)
	v_pk_fma_f32 v[12:13], v[12:13], v[72:73], v[176:177]
	v_pk_fma_f32 v[14:15], v[14:15], v[74:75], v[178:179]
	global_store_dwordx4 v238, v[12:15], s[94:95] offset:64
	v_pk_fma_f32 v[2:3], v[12:13], v[12:13], v[2:3]
	v_pk_fma_f32 v[2:3], v[14:15], v[14:15], v[2:3]
	v_pk_mul_f32 v[176:177], v[12:13], v[96:97]
	v_pk_mul_f32 v[178:179], v[14:15], v[98:99]
	v_cvt_pk_bf16_f32 v226, v176, v177
	v_cvt_pk_bf16_f32 v227, v178, v179
	s_nop 1
	v_permlane16_swap_b32 v224, v226
	v_permlane16_swap_b32 v225, v227
	global_store_dwordx4 v239, v[224:227], s[10:11] offset:0
	s_waitcnt vmcnt(19)
	v_pk_fma_f32 v[8:9], v[8:9], v[76:77], v[180:181]
	v_pk_fma_f32 v[10:11], v[10:11], v[78:79], v[182:183]
	global_store_dwordx4 v238, v[8:11], s[94:95] offset:512
	v_pk_fma_f32 v[2:3], v[8:9], v[8:9], v[2:3]
	v_pk_fma_f32 v[2:3], v[10:11], v[10:11], v[2:3]
	v_pk_mul_f32 v[180:181], v[8:9], v[100:101]
	v_pk_mul_f32 v[182:183], v[10:11], v[102:103]
	v_cvt_pk_bf16_f32 v216, v180, v181
	v_cvt_pk_bf16_f32 v217, v182, v183
	s_waitcnt vmcnt(18)
	v_pk_fma_f32 v[4:5], v[4:5], v[80:81], v[184:185]
	v_pk_fma_f32 v[6:7], v[6:7], v[82:83], v[186:187]
	global_store_dwordx4 v238, v[4:7], s[94:95] offset:576
	v_pk_fma_f32 v[2:3], v[4:5], v[4:5], v[2:3]
	v_pk_fma_f32 v[2:3], v[6:7], v[6:7], v[2:3]
	v_pk_mul_f32 v[184:185], v[4:5], v[84:85]
	v_pk_mul_f32 v[186:187], v[6:7], v[86:87]
	v_cvt_pk_bf16_f32 v218, v184, v185
	v_cvt_pk_bf16_f32 v219, v186, v187
	s_nop 1
	v_permlane16_swap_b32 v216, v218
	v_permlane16_swap_b32 v217, v219
	global_store_dwordx4 v239, v[216:219], s[10:11] offset:256
	v_add_f32_e32 v16, v2, v3
	v_xor_b32_e32 v236, 16, v250
	v_lshlrev_b32_e32 v236, 2, v236
	v_xor_b32_e32 v237, 32, v250
	v_lshlrev_b32_e32 v237, 2, v237
	ds_bpermute_b32 v164, v236, v160
	ds_bpermute_b32 v165, v236, v152
	ds_bpermute_b32 v166, v236, v136
	ds_bpermute_b32 v167, v236, v120
	ds_bpermute_b32 v168, v236, v64
	ds_bpermute_b32 v169, v236, v48
	ds_bpermute_b32 v170, v236, v32
	ds_bpermute_b32 v171, v236, v16
	s_waitcnt lgkmcnt(0)
	v_add_f32_e32 v160, v160, v164
	v_add_f32_e32 v152, v152, v165
	v_add_f32_e32 v136, v136, v166
	v_add_f32_e32 v120, v120, v167
	v_add_f32_e32 v64, v64, v168
	v_add_f32_e32 v48, v48, v169
	v_add_f32_e32 v32, v32, v170
	v_add_f32_e32 v16, v16, v171
	ds_bpermute_b32 v164, v237, v160
	ds_bpermute_b32 v165, v237, v152
	ds_bpermute_b32 v166, v237, v136
	ds_bpermute_b32 v167, v237, v120
	ds_bpermute_b32 v168, v237, v64
	ds_bpermute_b32 v169, v237, v48
	ds_bpermute_b32 v170, v237, v32
	ds_bpermute_b32 v171, v237, v16
	s_waitcnt lgkmcnt(0)
	v_add_f32_e32 v160, v160, v164
	v_add_f32_e32 v152, v152, v165
	v_add_f32_e32 v136, v136, v166
	v_add_f32_e32 v120, v120, v167
	v_add_f32_e32 v64, v64, v168
	v_add_f32_e32 v48, v48, v169
	v_add_f32_e32 v32, v32, v170
	v_add_f32_e32 v16, v16, v171
	s_and_saveexec_b64 s[4:5], s[0:1]
	global_atomic_add_f32 v251, v160, s[12:13] offset:0
	global_atomic_add_f32 v251, v152, s[12:13] offset:64
	global_atomic_add_f32 v251, v136, s[12:13] offset:128
	global_atomic_add_f32 v251, v120, s[12:13] offset:192
	global_atomic_add_f32 v251, v64, s[12:13] offset:512
	global_atomic_add_f32 v251, v48, s[12:13] offset:576
	global_atomic_add_f32 v251, v32, s[12:13] offset:640
	global_atomic_add_f32 v251, v16, s[12:13] offset:704
	s_or_b64 exec, exec, s[4:5]
	s_branch .Lp6_done
.Lp6_quart:
	v_mov_b32_e32 v236, v1
	global_load_dwordx4 v[164:167], v236, s[82:83] offset:0 nt
	global_load_dwordx4 v[168:171], v236, s[82:83] offset:64 nt
	v_add_u32_e32 v237, 0x20000, v1
	global_load_dwordx4 v[172:175], v237, s[82:83] offset:0 nt
	global_load_dwordx4 v[176:179], v237, s[82:83] offset:64 nt
	v_add_u32_e32 v236, 0x40000, v1
	global_load_dwordx4 v[180:183], v236, s[82:83] offset:0 nt
	global_load_dwordx4 v[184:187], v236, s[82:83] offset:64 nt
	v_add_u32_e32 v237, 0x60000, v1
	global_load_dwordx4 v[188:191], v237, s[82:83] offset:0 nt
	global_load_dwordx4 v[192:195], v237, s[82:83] offset:64 nt
	s_waitcnt vmcnt(7)
	v_mov_b32_e32 v238, v1
	v_mov_b32_e32 v239, v240
	v_pk_fma_f32 v[160:161], v[160:161], v[68:69], v[164:165]
	v_pk_fma_f32 v[162:163], v[162:163], v[70:71], v[166:167]
	global_store_dwordx4 v238, v[160:163], s[94:95] offset:0
	v_pk_mul_f32 v[2:3], v[160:161], v[160:161]
	v_pk_fma_f32 v[2:3], v[162:163], v[162:163], v[2:3]
	v_pk_mul_f32 v[164:165], v[160:161], v[92:93]
	v_pk_mul_f32 v[166:167], v[162:163], v[94:95]
	v_cvt_pk_bf16_f32 v216, v164, v165
	v_cvt_pk_bf16_f32 v217, v166, v167
	s_waitcnt vmcnt(7)
	v_pk_fma_f32 v[156:157], v[156:157], v[72:73], v[168:169]
	v_pk_fma_f32 v[158:159], v[158:159], v[74:75], v[170:171]
	global_store_dwordx4 v238, v[156:159], s[94:95] offset:64
	v_pk_fma_f32 v[2:3], v[156:157], v[156:157], v[2:3]
	v_pk_fma_f32 v[2:3], v[158:159], v[158:159], v[2:3]
	v_pk_mul_f32 v[168:169], v[156:157], v[96:97]
	v_pk_mul_f32 v[170:171], v[158:159], v[98:99]
	v_cvt_pk_bf16_f32 v218, v168, v169
	v_cvt_pk_bf16_f32 v219, v170, v171
	s_nop 1
	v_permlane16_swap_b32 v216, v218
	v_permlane16_swap_b32 v217, v219
	global_store_dwordx4 v239, v[216:219], s[10:11] offset:0
	v_add_f32_e32 v160, v2, v3
	s_waitcnt vmcnt(8)
	v_add_u32_e32 v238, 0x20000, v1
	v_add_u32_e32 v239, 0x10000, v240
	v_pk_fma_f32 v[152:153], v[152:153], v[68:69], v[172:173]
	v_pk_fma_f32 v[154:155], v[154:155], v[70:71], v[174:175]
	global_store_dwordx4 v238, v[152:155], s[94:95] offset:0
	v_pk_mul_f32 v[2:3], v[152:153], v[152:153]
	v_pk_fma_f32 v[2:3], v[154:155], v[154:155], v[2:3]
	v_pk_mul_f32 v[172:173], v[152:153], v[92:93]
	v_pk_mul_f32 v[174:175], v[154:155], v[94:95]
	v_cvt_pk_bf16_f32 v220, v172, v173
	v_cvt_pk_bf16_f32 v221, v174, v175
	s_waitcnt vmcnt(8)
	v_pk_fma_f32 v[148:149], v[148:149], v[72:73], v[176:177]
	v_pk_fma_f32 v[150:151], v[150:151], v[74:75], v[178:179]
	global_store_dwordx4 v238, v[148:151], s[94:95] offset:64
	v_pk_fma_f32 v[2:3], v[148:149], v[148:149], v[2:3]
	v_pk_fma_f32 v[2:3], v[150:151], v[150:151], v[2:3]
	v_pk_mul_f32 v[176:177], v[148:149], v[96:97]
	v_pk_mul_f32 v[178:179], v[150:151], v[98:99]
	v_cvt_pk_bf16_f32 v222, v176, v177
	v_cvt_pk_bf16_f32 v223, v178, v179
	s_nop 1
	v_permlane16_swap_b32 v220, v222
	v_permlane16_swap_b32 v221, v223
	global_store_dwordx4 v239, v[220:223], s[10:11] offset:0
	v_add_f32_e32 v152, v2, v3
	s_waitcnt vmcnt(9)
	v_add_u32_e32 v238, 0x40000, v1
	v_add_u32_e32 v239, 0x20000, v240
	v_pk_fma_f32 v[136:137], v[136:137], v[68:69], v[180:181]
	v_pk_fma_f32 v[138:139], v[138:139], v[70:71], v[182:183]
	global_store_dwordx4 v238, v[136:139], s[94:95] offset:0
	v_pk_mul_f32 v[2:3], v[136:137], v[136:137]
	v_pk_fma_f32 v[2:3], v[138:139], v[138:139], v[2:3]
	v_pk_mul_f32 v[180:181], v[136:137], v[92:93]
	v_pk_mul_f32 v[182:183], v[138:139], v[94:95]
	v_cvt_pk_bf16_f32 v224, v180, v181
	v_cvt_pk_bf16_f32 v225, v182, v183
	s_waitcnt vmcnt(9)
	v_pk_fma_f32 v[132:133], v[132:133], v[72:73], v[184:185]
	v_pk_fma_f32 v[134:135], v[134:135], v[74:75], v[186:187]
	global_store_dwordx4 v238, v[132:135], s[94:95] offset:64
	v_pk_fma_f32 v[2:3], v[132:133], v[132:133], v[2:3]
	v_pk_fma_f32 v[2:3], v[134:135], v[134:135], v[2:3]
	v_pk_mul_f32 v[184:185], v[132:133], v[96:97]
	v_pk_mul_f32 v[186:187], v[134:135], v[98:99]
	v_cvt_pk_bf16_f32 v226, v184, v185
	v_cvt_pk_bf16_f32 v227, v186, v187
	s_nop 1
	v_permlane16_swap_b32 v224, v226
	v_permlane16_swap_b32 v225, v227
	global_store_dwordx4 v239, v[224:227], s[10:11] offset:0
	v_add_f32_e32 v136, v2, v3
	s_waitcnt vmcnt(10)
	v_add_u32_e32 v238, 0x60000, v1
	v_add_u32_e32 v239, 0x30000, v240
	v_pk_fma_f32 v[120:121], v[120:121], v[68:69], v[188:189]
	v_pk_fma_f32 v[122:123], v[122:123], v[70:71], v[190:191]
	global_store_dwordx4 v238, v[120:123], s[94:95] offset:0
	v_pk_mul_f32 v[2:3], v[120:121], v[120:121]
	v_pk_fma_f32 v[2:3], v[122:123], v[122:123], v[2:3]
	v_pk_mul_f32 v[188:189], v[120:121], v[92:93]
	v_pk_mul_f32 v[190:191], v[122:123], v[94:95]
	v_cvt_pk_bf16_f32 v216, v188, v189
	v_cvt_pk_bf16_f32 v217, v190, v191
	s_waitcnt vmcnt(10)
	v_pk_fma_f32 v[112:113], v[112:113], v[72:73], v[192:193]
	v_pk_fma_f32 v[114:115], v[114:115], v[74:75], v[194:195]
	global_store_dwordx4 v238, v[112:115], s[94:95] offset:64
	v_pk_fma_f32 v[2:3], v[112:113], v[112:113], v[2:3]
	v_pk_fma_f32 v[2:3], v[114:115], v[114:115], v[2:3]
	v_pk_mul_f32 v[192:193], v[112:113], v[96:97]
	v_pk_mul_f32 v[194:195], v[114:115], v[98:99]
	v_cvt_pk_bf16_f32 v218, v192, v193
	v_cvt_pk_bf16_f32 v219, v194, v195
	s_nop 1
	v_permlane16_swap_b32 v216, v218
	v_permlane16_swap_b32 v217, v219
	global_store_dwordx4 v239, v[216:219], s[10:11] offset:0
	v_add_f32_e32 v120, v2, v3
	v_xor_b32_e32 v236, 16, v250
	v_lshlrev_b32_e32 v236, 2, v236
	v_xor_b32_e32 v237, 32, v250
	v_lshlrev_b32_e32 v237, 2, v237
	ds_bpermute_b32 v164, v236, v160
	ds_bpermute_b32 v165, v236, v152
	ds_bpermute_b32 v166, v236, v136
	ds_bpermute_b32 v167, v236, v120
	s_waitcnt lgkmcnt(0)
	v_add_f32_e32 v160, v160, v164
	v_add_f32_e32 v152, v152, v165
	v_add_f32_e32 v136, v136, v166
	v_add_f32_e32 v120, v120, v167
	ds_bpermute_b32 v164, v237, v160
	ds_bpermute_b32 v165, v237, v152
	ds_bpermute_b32 v166, v237, v136
	ds_bpermute_b32 v167, v237, v120
	s_waitcnt lgkmcnt(0)
	v_add_f32_e32 v160, v160, v164
	v_add_f32_e32 v152, v152, v165
	v_add_f32_e32 v136, v136, v166
	v_add_f32_e32 v120, v120, v167
	s_and_saveexec_b64 s[4:5], s[0:1]
	global_atomic_add_f32 v251, v160, s[12:13] offset:0
	global_atomic_add_f32 v251, v152, s[12:13] offset:64
	global_atomic_add_f32 v251, v136, s[12:13] offset:128
	global_atomic_add_f32 v251, v120, s[12:13] offset:192
	s_or_b64 exec, exec, s[4:5]
.Lp6_done:
	v_readlane_b32 s52, v253, 26
	v_readlane_b32 s53, v253, 27
	v_readlane_b32 s87, v253, 13
	v_readlane_b32 s88, v253, 14
	v_readlane_b32 s89, v253, 15

.LBB0_1629:
	s_sub_i32 s16, s56, 32
	s_lshr_b32 s16, s16, 2
	s_mulk_i32 s16, 0x3000
	s_lshl_b32 s30, s56, 8
	s_lshl_b32 s26, s58, 8
	s_addk_i32 s16, 0x3000
	s_cmp_gt_i32 s56, 31
	s_cselect_b32 s16, s16, 0
	s_lshl_b64 s[34:35], s[16:17], 2
	v_readlane_b32 s0, v253, 22
	v_or_b32_e32 v156, s26, v221
	v_readlane_b32 s1, v253, 23
	s_add_u32 s34, s0, s34
	s_addc_u32 s35, s1, s35
	v_ashrrev_i32_e32 v157, 31, v156
	v_lshl_add_u64 v[128:129], v[156:157], 2, s[34:35]
	s_mov_b64 s[34:35], 0xa000
	v_add_u32_e32 v158, s30, v219
	v_lshl_add_u64 v[154:155], v[128:129], 0, s[34:35]
	s_cmp_lt_i32 s91, 1
	s_mov_b64 s[34:35], -1
	v_readlane_b32 s2, v253, 24
	v_readlane_b32 s3, v253, 25
	s_cbranch_scc0 .LBB0_1662
	v_readlane_b32 s8, v253, 20
	v_readlane_b32 s9, v253, 21
	s_lshl_b32 s10, s56, 21
	s_lshl_b32 s11, s58, 10
	s_add_u32 s10, s10, s11
	s_add_u32 s8, s8, s10
	s_addc_u32 s9, s9, 0
	global_load_dwordx4 v[132:135], v[154:155], off
	global_load_dwordx4 v[128:131], v[154:155], off offset:64
	global_load_dwordx4 v[140:143], v[154:155], off offset:512
	global_load_dwordx4 v[136:139], v[154:155], off offset:576
	v_lshlrev_b32_e32 v160, 2, v148
	v_mov_b32_e32 v162, v160
	global_load_dwordx4 v[176:179], v162, s[8:9] offset:0
	global_load_dwordx4 v[180:183], v162, s[8:9] offset:64
	global_load_dwordx4 v[184:187], v162, s[8:9] offset:512
	global_load_dwordx4 v[188:191], v162, s[8:9] offset:576
	v_add_u32_e32 v163, 0x20000, v160
	global_load_dwordx4 v[192:195], v163, s[8:9] offset:0
	global_load_dwordx4 v[196:199], v163, s[8:9] offset:64
	global_load_dwordx4 v[200:203], v163, s[8:9] offset:512
	global_load_dwordx4 v[204:207], v163, s[8:9] offset:576
	v_add_u32_e32 v162, 0x40000, v160
	global_load_dwordx4 v[208:211], v162, s[8:9] offset:0
	global_load_dwordx4 v[212:215], v162, s[8:9] offset:64
	global_load_dwordx4 v[232:235], v162, s[8:9] offset:512
	global_load_dwordx4 v[236:239], v162, s[8:9] offset:576
	v_add_u32_e32 v163, 0x60000, v160
	global_load_dwordx4 v[244:247], v163, s[8:9] offset:0
	global_load_dwordx4 v[248:251], v163, s[8:9] offset:64
	s_waitcnt vmcnt(13)
	v_pk_fma_f32 v[124:125], v[124:125], v[132:133], v[176:177]
	v_pk_fma_f32 v[126:127], v[126:127], v[134:135], v[178:179]
	v_pk_mul_f32 v[174:175], v[124:125], v[124:125]
	v_pk_fma_f32 v[174:175], v[126:127], v[126:127], v[174:175]
	global_load_dwordx4 v[176:179], v163, s[8:9] offset:512
	s_waitcnt vmcnt(13)
	v_pk_fma_f32 v[120:121], v[120:121], v[128:129], v[180:181]
	v_pk_fma_f32 v[122:123], v[122:123], v[130:131], v[182:183]
	v_pk_fma_f32 v[174:175], v[120:121], v[120:121], v[174:175]
	v_pk_fma_f32 v[174:175], v[122:123], v[122:123], v[174:175]
	global_load_dwordx4 v[180:183], v163, s[8:9] offset:576
	s_waitcnt vmcnt(13)
	v_pk_fma_f32 v[116:117], v[116:117], v[140:141], v[184:185]
	v_pk_fma_f32 v[118:119], v[118:119], v[142:143], v[186:187]
	v_pk_fma_f32 v[174:175], v[116:117], v[116:117], v[174:175]
	v_pk_fma_f32 v[174:175], v[118:119], v[118:119], v[174:175]
	v_add_u32_e32 v162, 0x100000, v160
	global_load_dwordx4 v[184:187], v162, s[8:9] offset:0
	s_waitcnt vmcnt(13)
	v_pk_fma_f32 v[108:109], v[108:109], v[136:137], v[188:189]
	v_pk_fma_f32 v[110:111], v[110:111], v[138:139], v[190:191]
	v_pk_fma_f32 v[174:175], v[108:109], v[108:109], v[174:175]
	v_pk_fma_f32 v[174:175], v[110:111], v[110:111], v[174:175]
	v_add_f32_e32 v165, v174, v175
	global_load_dwordx4 v[188:191], v162, s[8:9] offset:64
	s_waitcnt vmcnt(13)
	v_pk_fma_f32 v[112:113], v[112:113], v[132:133], v[192:193]
	v_pk_fma_f32 v[114:115], v[114:115], v[134:135], v[194:195]
	v_pk_mul_f32 v[174:175], v[112:113], v[112:113]
	v_pk_fma_f32 v[174:175], v[114:115], v[114:115], v[174:175]
	global_load_dwordx4 v[192:195], v162, s[8:9] offset:512
	s_waitcnt vmcnt(13)
	v_pk_fma_f32 v[104:105], v[104:105], v[128:129], v[196:197]
	v_pk_fma_f32 v[106:107], v[106:107], v[130:131], v[198:199]
	v_pk_fma_f32 v[174:175], v[104:105], v[104:105], v[174:175]
	v_pk_fma_f32 v[174:175], v[106:107], v[106:107], v[174:175]
	global_load_dwordx4 v[196:199], v162, s[8:9] offset:576
	s_waitcnt vmcnt(13)
	v_pk_fma_f32 v[100:101], v[100:101], v[140:141], v[200:201]
	v_pk_fma_f32 v[102:103], v[102:103], v[142:143], v[202:203]
	v_pk_fma_f32 v[174:175], v[100:101], v[100:101], v[174:175]
	v_pk_fma_f32 v[174:175], v[102:103], v[102:103], v[174:175]
	v_add_u32_e32 v163, 0x120000, v160
	global_load_dwordx4 v[200:203], v163, s[8:9] offset:0
	s_waitcnt vmcnt(13)
	v_pk_fma_f32 v[92:93], v[92:93], v[136:137], v[204:205]
	v_pk_fma_f32 v[94:95], v[94:95], v[138:139], v[206:207]
	v_pk_fma_f32 v[174:175], v[92:93], v[92:93], v[174:175]
	v_pk_fma_f32 v[174:175], v[94:95], v[94:95], v[174:175]
	v_add_f32_e32 v167, v174, v175
	global_load_dwordx4 v[204:207], v163, s[8:9] offset:64
	s_waitcnt vmcnt(13)
	v_pk_fma_f32 v[96:97], v[96:97], v[132:133], v[208:209]
	v_pk_fma_f32 v[98:99], v[98:99], v[134:135], v[210:211]
	v_pk_mul_f32 v[174:175], v[96:97], v[96:97]
	v_pk_fma_f32 v[174:175], v[98:99], v[98:99], v[174:175]
	global_load_dwordx4 v[208:211], v163, s[8:9] offset:512
	s_waitcnt vmcnt(13)
	v_pk_fma_f32 v[88:89], v[88:89], v[128:129], v[212:213]
	v_pk_fma_f32 v[90:91], v[90:91], v[130:131], v[214:215]
	v_pk_fma_f32 v[174:175], v[88:89], v[88:89], v[174:175]
	v_pk_fma_f32 v[174:175], v[90:91], v[90:91], v[174:175]
	global_load_dwordx4 v[212:215], v163, s[8:9] offset:576
	s_waitcnt vmcnt(13)
	v_pk_fma_f32 v[84:85], v[84:85], v[140:141], v[232:233]
	v_pk_fma_f32 v[86:87], v[86:87], v[142:143], v[234:235]
	v_pk_fma_f32 v[174:175], v[84:85], v[84:85], v[174:175]
	v_pk_fma_f32 v[174:175], v[86:87], v[86:87], v[174:175]
	v_add_u32_e32 v162, 0x140000, v160
	global_load_dwordx4 v[232:235], v162, s[8:9] offset:0
	s_waitcnt vmcnt(13)
	v_pk_fma_f32 v[76:77], v[76:77], v[136:137], v[236:237]
	v_pk_fma_f32 v[78:79], v[78:79], v[138:139], v[238:239]
	v_pk_fma_f32 v[174:175], v[76:77], v[76:77], v[174:175]
	v_pk_fma_f32 v[174:175], v[78:79], v[78:79], v[174:175]
	v_add_f32_e32 v168, v174, v175
	global_load_dwordx4 v[236:239], v162, s[8:9] offset:64
	s_waitcnt vmcnt(13)
	v_pk_fma_f32 v[80:81], v[80:81], v[132:133], v[244:245]
	v_pk_fma_f32 v[82:83], v[82:83], v[134:135], v[246:247]
	v_pk_mul_f32 v[174:175], v[80:81], v[80:81]
	v_pk_fma_f32 v[174:175], v[82:83], v[82:83], v[174:175]
	global_load_dwordx4 v[244:247], v162, s[8:9] offset:512
	s_waitcnt vmcnt(13)
	v_pk_fma_f32 v[72:73], v[72:73], v[128:129], v[248:249]
	v_pk_fma_f32 v[74:75], v[74:75], v[130:131], v[250:251]
	v_pk_fma_f32 v[174:175], v[72:73], v[72:73], v[174:175]
	v_pk_fma_f32 v[174:175], v[74:75], v[74:75], v[174:175]
	global_load_dwordx4 v[248:251], v162, s[8:9] offset:576
	s_waitcnt vmcnt(13)
	v_pk_fma_f32 v[68:69], v[68:69], v[140:141], v[176:177]
	v_pk_fma_f32 v[70:71], v[70:71], v[142:143], v[178:179]
	v_pk_fma_f32 v[174:175], v[68:69], v[68:69], v[174:175]
	v_pk_fma_f32 v[174:175], v[70:71], v[70:71], v[174:175]
	v_add_u32_e32 v163, 0x160000, v160
	global_load_dwordx4 v[176:179], v163, s[8:9] offset:0
	s_waitcnt vmcnt(13)
	v_pk_fma_f32 v[64:65], v[64:65], v[136:137], v[180:181]
	v_pk_fma_f32 v[66:67], v[66:67], v[138:139], v[182:183]
	v_pk_fma_f32 v[174:175], v[64:65], v[64:65], v[174:175]
	v_pk_fma_f32 v[174:175], v[66:67], v[66:67], v[174:175]
	v_add_f32_e32 v169, v174, v175
	global_load_dwordx4 v[180:183], v163, s[8:9] offset:64
	s_waitcnt vmcnt(13)
	v_pk_fma_f32 v[60:61], v[60:61], v[132:133], v[184:185]
	v_pk_fma_f32 v[62:63], v[62:63], v[134:135], v[186:187]
	v_pk_mul_f32 v[174:175], v[60:61], v[60:61]
	v_pk_fma_f32 v[174:175], v[62:63], v[62:63], v[174:175]
	global_load_dwordx4 v[184:187], v163, s[8:9] offset:512
	s_waitcnt vmcnt(13)
	v_pk_fma_f32 v[56:57], v[56:57], v[128:129], v[188:189]
	v_pk_fma_f32 v[58:59], v[58:59], v[130:131], v[190:191]
	v_pk_fma_f32 v[174:175], v[56:57], v[56:57], v[174:175]
	v_pk_fma_f32 v[174:175], v[58:59], v[58:59], v[174:175]
	global_load_dwordx4 v[188:191], v163, s[8:9] offset:576
	s_waitcnt vmcnt(13)
	v_pk_fma_f32 v[52:53], v[52:53], v[140:141], v[192:193]
	v_pk_fma_f32 v[54:55], v[54:55], v[142:143], v[194:195]
	v_pk_fma_f32 v[174:175], v[52:53], v[52:53], v[174:175]
	v_pk_fma_f32 v[174:175], v[54:55], v[54:55], v[174:175]
	s_waitcnt vmcnt(12)
	v_pk_fma_f32 v[44:45], v[44:45], v[136:137], v[196:197]
	v_pk_fma_f32 v[46:47], v[46:47], v[138:139], v[198:199]
	v_pk_fma_f32 v[174:175], v[44:45], v[44:45], v[174:175]
	v_pk_fma_f32 v[174:175], v[46:47], v[46:47], v[174:175]
	v_add_f32_e32 v170, v174, v175
	s_waitcnt vmcnt(11)
	v_pk_fma_f32 v[48:49], v[48:49], v[132:133], v[200:201]
	v_pk_fma_f32 v[50:51], v[50:51], v[134:135], v[202:203]
	v_pk_mul_f32 v[174:175], v[48:49], v[48:49]
	v_pk_fma_f32 v[174:175], v[50:51], v[50:51], v[174:175]
	s_waitcnt vmcnt(10)
	v_pk_fma_f32 v[40:41], v[40:41], v[128:129], v[204:205]
	v_pk_fma_f32 v[42:43], v[42:43], v[130:131], v[206:207]
	v_pk_fma_f32 v[174:175], v[40:41], v[40:41], v[174:175]
	v_pk_fma_f32 v[174:175], v[42:43], v[42:43], v[174:175]
	s_waitcnt vmcnt(9)
	v_pk_fma_f32 v[36:37], v[36:37], v[140:141], v[208:209]
	v_pk_fma_f32 v[38:39], v[38:39], v[142:143], v[210:211]
	v_pk_fma_f32 v[174:175], v[36:37], v[36:37], v[174:175]
	v_pk_fma_f32 v[174:175], v[38:39], v[38:39], v[174:175]
	s_waitcnt vmcnt(8)
	v_pk_fma_f32 v[28:29], v[28:29], v[136:137], v[212:213]
	v_pk_fma_f32 v[30:31], v[30:31], v[138:139], v[214:215]
	v_pk_fma_f32 v[174:175], v[28:29], v[28:29], v[174:175]
	v_pk_fma_f32 v[174:175], v[30:31], v[30:31], v[174:175]
	v_add_f32_e32 v171, v174, v175
	s_waitcnt vmcnt(7)
	v_pk_fma_f32 v[32:33], v[32:33], v[132:133], v[232:233]
	v_pk_fma_f32 v[34:35], v[34:35], v[134:135], v[234:235]
	v_pk_mul_f32 v[174:175], v[32:33], v[32:33]
	v_pk_fma_f32 v[174:175], v[34:35], v[34:35], v[174:175]
	s_waitcnt vmcnt(6)
	v_pk_fma_f32 v[24:25], v[24:25], v[128:129], v[236:237]
	v_pk_fma_f32 v[26:27], v[26:27], v[130:131], v[238:239]
	v_pk_fma_f32 v[174:175], v[24:25], v[24:25], v[174:175]
	v_pk_fma_f32 v[174:175], v[26:27], v[26:27], v[174:175]
	s_waitcnt vmcnt(5)
	v_pk_fma_f32 v[20:21], v[20:21], v[140:141], v[244:245]
	v_pk_fma_f32 v[22:23], v[22:23], v[142:143], v[246:247]
	v_pk_fma_f32 v[174:175], v[20:21], v[20:21], v[174:175]
	v_pk_fma_f32 v[174:175], v[22:23], v[22:23], v[174:175]
	s_waitcnt vmcnt(4)
	v_pk_fma_f32 v[12:13], v[12:13], v[136:137], v[248:249]
	v_pk_fma_f32 v[14:15], v[14:15], v[138:139], v[250:251]
	v_pk_fma_f32 v[174:175], v[12:13], v[12:13], v[174:175]
	v_pk_fma_f32 v[174:175], v[14:15], v[14:15], v[174:175]
	v_add_f32_e32 v172, v174, v175
	s_waitcnt vmcnt(3)
	v_pk_fma_f32 v[16:17], v[16:17], v[132:133], v[176:177]
	v_pk_fma_f32 v[18:19], v[18:19], v[134:135], v[178:179]
	v_pk_mul_f32 v[174:175], v[16:17], v[16:17]
	v_pk_fma_f32 v[174:175], v[18:19], v[18:19], v[174:175]
	s_waitcnt vmcnt(2)
	v_pk_fma_f32 v[8:9], v[8:9], v[128:129], v[180:181]
	v_pk_fma_f32 v[10:11], v[10:11], v[130:131], v[182:183]
	v_pk_fma_f32 v[174:175], v[8:9], v[8:9], v[174:175]
	v_pk_fma_f32 v[174:175], v[10:11], v[10:11], v[174:175]
	s_waitcnt vmcnt(1)
	v_pk_fma_f32 v[4:5], v[4:5], v[140:141], v[184:185]
	v_pk_fma_f32 v[6:7], v[6:7], v[142:143], v[186:187]
	v_pk_fma_f32 v[174:175], v[4:5], v[4:5], v[174:175]
	v_pk_fma_f32 v[174:175], v[6:7], v[6:7], v[174:175]
	s_waitcnt vmcnt(0)
	v_pk_fma_f32 v[0:1], v[0:1], v[136:137], v[188:189]
	v_pk_fma_f32 v[2:3], v[2:3], v[138:139], v[190:191]
	v_pk_fma_f32 v[174:175], v[0:1], v[0:1], v[174:175]
	v_pk_fma_f32 v[174:175], v[2:3], v[2:3], v[174:175]
	v_add_f32_e32 v161, v174, v175
	v_xor_b32_e32 v162, 16, v230
	v_lshlrev_b32_e32 v162, 2, v162
	v_xor_b32_e32 v163, 32, v230
	v_lshlrev_b32_e32 v163, 2, v163
	ds_bpermute_b32 v176, v162, v165
	ds_bpermute_b32 v177, v162, v167
	ds_bpermute_b32 v178, v162, v168
	ds_bpermute_b32 v179, v162, v169
	ds_bpermute_b32 v180, v162, v170
	ds_bpermute_b32 v181, v162, v171
	ds_bpermute_b32 v182, v162, v172
	ds_bpermute_b32 v183, v162, v161
	s_waitcnt lgkmcnt(0)
	v_add_f32_e32 v165, v165, v176
	v_add_f32_e32 v167, v167, v177
	v_add_f32_e32 v168, v168, v178
	v_add_f32_e32 v169, v169, v179
	v_add_f32_e32 v170, v170, v180
	v_add_f32_e32 v171, v171, v181
	v_add_f32_e32 v172, v172, v182
	v_add_f32_e32 v161, v161, v183
	ds_bpermute_b32 v176, v163, v165
	ds_bpermute_b32 v177, v163, v167
	ds_bpermute_b32 v178, v163, v168
	ds_bpermute_b32 v179, v163, v169
	ds_bpermute_b32 v180, v163, v170
	ds_bpermute_b32 v181, v163, v171
	ds_bpermute_b32 v182, v163, v172
	ds_bpermute_b32 v183, v163, v161
	s_waitcnt lgkmcnt(0)
	v_add_f32_e32 v165, v165, v176
	v_add_f32_e32 v167, v167, v177
	v_add_f32_e32 v168, v168, v178
	v_add_f32_e32 v169, v169, v179
	v_add_f32_e32 v170, v170, v180
	v_add_f32_e32 v171, v171, v181
	v_add_f32_e32 v172, v172, v182
	v_add_f32_e32 v161, v161, v183
	v_mov_b32_e32 v128, v161
	s_and_saveexec_b64 s[26:27], s[40:41]
	s_cbranch_execz .Lp8_noatom
	v_ashrrev_i32_e32 v159, 31, v158
	v_lshl_add_u64 v[162:163], v[158:159], 2, s[20:21]
	global_atomic_add_f32 v[162:163], v165, off offset:0
	global_atomic_add_f32 v[162:163], v167, off offset:64
	global_atomic_add_f32 v[162:163], v168, off offset:128
	global_atomic_add_f32 v[162:163], v169, off offset:192
	global_atomic_add_f32 v[162:163], v170, off offset:512
	global_atomic_add_f32 v[162:163], v171, off offset:576
	global_atomic_add_f32 v[162:163], v172, off offset:640
	global_atomic_add_f32 v[162:163], v128, off offset:704

.LBB0_1667:
	s_or_b64 exec, exec, s[26:27]
	v_readlane_b32 s0, v253, 6
	v_readlane_b32 s12, v253, 18
	v_readlane_b32 s13, v253, 19
	s_waitcnt lgkmcnt(0)
	s_waitcnt lgkmcnt(0)
	s_barrier
	v_lshl_add_u64 v[128:129], v[156:157], 2, s[12:13]
	global_load_dwordx4 v[132:135], v[128:129], off
	global_load_dwordx4 v[136:139], v[128:129], off offset:64
	global_load_dwordx4 v[140:143], v[128:129], off offset:512
	global_load_dwordx4 v[160:163], v[128:129], off offset:576
	ds_read_b32 v164, v223 offset:0
	ds_read_b32 v166, v223 offset:64
	ds_read_b32 v168, v223 offset:128
	ds_read_b32 v170, v223 offset:192
	ds_read_b32 v172, v223 offset:512
	ds_read_b32 v174, v223 offset:576
	ds_read_b32 v176, v223 offset:640
	ds_read_b32 v178, v223 offset:704
	v_lshlrev_b32_e32 v180, 2, v148
	s_waitcnt vmcnt(0) lgkmcnt(0)
	v_mov_b32_e32 v181, v180
	v_pk_mul_f32 v[124:125], v[124:125], v[164:165] op_sel_hi:[1,0]
	v_pk_mul_f32 v[126:127], v[126:127], v[164:165] op_sel_hi:[1,0]
	v_pk_mul_f32 v[124:125], v[132:133], v[124:125]
	v_pk_mul_f32 v[126:127], v[134:135], v[126:127]
	global_store_dwordx4 v181, v[124:127], s[8:9] offset:0 nt
	v_pk_mul_f32 v[120:121], v[120:121], v[164:165] op_sel_hi:[1,0]
	v_pk_mul_f32 v[122:123], v[122:123], v[164:165] op_sel_hi:[1,0]
	v_pk_mul_f32 v[120:121], v[136:137], v[120:121]
	v_pk_mul_f32 v[122:123], v[138:139], v[122:123]
	global_store_dwordx4 v181, v[120:123], s[8:9] offset:64 nt
	v_pk_mul_f32 v[116:117], v[116:117], v[164:165] op_sel_hi:[1,0]
	v_pk_mul_f32 v[118:119], v[118:119], v[164:165] op_sel_hi:[1,0]
	v_pk_mul_f32 v[116:117], v[140:141], v[116:117]
	v_pk_mul_f32 v[118:119], v[142:143], v[118:119]
	global_store_dwordx4 v181, v[116:119], s[8:9] offset:512 nt
	v_pk_mul_f32 v[108:109], v[108:109], v[164:165] op_sel_hi:[1,0]
	v_pk_mul_f32 v[110:111], v[110:111], v[164:165] op_sel_hi:[1,0]
	v_pk_mul_f32 v[108:109], v[160:161], v[108:109]
	v_pk_mul_f32 v[110:111], v[162:163], v[110:111]
	global_store_dwordx4 v181, v[108:111], s[8:9] offset:576 nt
	v_add_u32_e32 v182, 0x20000, v180
	v_pk_mul_f32 v[112:113], v[112:113], v[166:167] op_sel_hi:[1,0]
	v_pk_mul_f32 v[114:115], v[114:115], v[166:167] op_sel_hi:[1,0]
	v_pk_mul_f32 v[112:113], v[132:133], v[112:113]
	v_pk_mul_f32 v[114:115], v[134:135], v[114:115]
	global_store_dwordx4 v182, v[112:115], s[8:9] offset:0 nt
	v_pk_mul_f32 v[104:105], v[104:105], v[166:167] op_sel_hi:[1,0]
	v_pk_mul_f32 v[106:107], v[106:107], v[166:167] op_sel_hi:[1,0]
	v_pk_mul_f32 v[104:105], v[136:137], v[104:105]
	v_pk_mul_f32 v[106:107], v[138:139], v[106:107]
	global_store_dwordx4 v182, v[104:107], s[8:9] offset:64 nt
	v_pk_mul_f32 v[100:101], v[100:101], v[166:167] op_sel_hi:[1,0]
	v_pk_mul_f32 v[102:103], v[102:103], v[166:167] op_sel_hi:[1,0]
	v_pk_mul_f32 v[100:101], v[140:141], v[100:101]
	v_pk_mul_f32 v[102:103], v[142:143], v[102:103]
	global_store_dwordx4 v182, v[100:103], s[8:9] offset:512 nt
	v_pk_mul_f32 v[92:93], v[92:93], v[166:167] op_sel_hi:[1,0]
	v_pk_mul_f32 v[94:95], v[94:95], v[166:167] op_sel_hi:[1,0]
	v_pk_mul_f32 v[92:93], v[160:161], v[92:93]
	v_pk_mul_f32 v[94:95], v[162:163], v[94:95]
	global_store_dwordx4 v182, v[92:95], s[8:9] offset:576 nt
	v_add_u32_e32 v181, 0x40000, v180
	v_pk_mul_f32 v[96:97], v[96:97], v[168:169] op_sel_hi:[1,0]
	v_pk_mul_f32 v[98:99], v[98:99], v[168:169] op_sel_hi:[1,0]
	v_pk_mul_f32 v[96:97], v[132:133], v[96:97]
	v_pk_mul_f32 v[98:99], v[134:135], v[98:99]
	global_store_dwordx4 v181, v[96:99], s[8:9] offset:0 nt
	v_pk_mul_f32 v[88:89], v[88:89], v[168:169] op_sel_hi:[1,0]
	v_pk_mul_f32 v[90:91], v[90:91], v[168:169] op_sel_hi:[1,0]
	v_pk_mul_f32 v[88:89], v[136:137], v[88:89]
	v_pk_mul_f32 v[90:91], v[138:139], v[90:91]
	global_store_dwordx4 v181, v[88:91], s[8:9] offset:64 nt
	v_pk_mul_f32 v[84:85], v[84:85], v[168:169] op_sel_hi:[1,0]
	v_pk_mul_f32 v[86:87], v[86:87], v[168:169] op_sel_hi:[1,0]
	v_pk_mul_f32 v[84:85], v[140:141], v[84:85]
	v_pk_mul_f32 v[86:87], v[142:143], v[86:87]
	global_store_dwordx4 v181, v[84:87], s[8:9] offset:512 nt
	v_pk_mul_f32 v[76:77], v[76:77], v[168:169] op_sel_hi:[1,0]
	v_pk_mul_f32 v[78:79], v[78:79], v[168:169] op_sel_hi:[1,0]
	v_pk_mul_f32 v[76:77], v[160:161], v[76:77]
	v_pk_mul_f32 v[78:79], v[162:163], v[78:79]
	global_store_dwordx4 v181, v[76:79], s[8:9] offset:576 nt
	v_add_u32_e32 v182, 0x60000, v180
	v_pk_mul_f32 v[80:81], v[80:81], v[170:171] op_sel_hi:[1,0]
	v_pk_mul_f32 v[82:83], v[82:83], v[170:171] op_sel_hi:[1,0]
	v_pk_mul_f32 v[80:81], v[132:133], v[80:81]
	v_pk_mul_f32 v[82:83], v[134:135], v[82:83]
	global_store_dwordx4 v182, v[80:83], s[8:9] offset:0 nt
	v_pk_mul_f32 v[72:73], v[72:73], v[170:171] op_sel_hi:[1,0]
	v_pk_mul_f32 v[74:75], v[74:75], v[170:171] op_sel_hi:[1,0]
	v_pk_mul_f32 v[72:73], v[136:137], v[72:73]
	v_pk_mul_f32 v[74:75], v[138:139], v[74:75]
	global_store_dwordx4 v182, v[72:75], s[8:9] offset:64 nt
	v_pk_mul_f32 v[68:69], v[68:69], v[170:171] op_sel_hi:[1,0]
	v_pk_mul_f32 v[70:71], v[70:71], v[170:171] op_sel_hi:[1,0]
	v_pk_mul_f32 v[68:69], v[140:141], v[68:69]
	v_pk_mul_f32 v[70:71], v[142:143], v[70:71]
	global_store_dwordx4 v182, v[68:71], s[8:9] offset:512 nt
	v_pk_mul_f32 v[64:65], v[64:65], v[170:171] op_sel_hi:[1,0]
	v_pk_mul_f32 v[66:67], v[66:67], v[170:171] op_sel_hi:[1,0]
	v_pk_mul_f32 v[64:65], v[160:161], v[64:65]
	v_pk_mul_f32 v[66:67], v[162:163], v[66:67]
	global_store_dwordx4 v182, v[64:67], s[8:9] offset:576 nt
	v_add_u32_e32 v181, 0x100000, v180
	v_pk_mul_f32 v[60:61], v[60:61], v[172:173] op_sel_hi:[1,0]
	v_pk_mul_f32 v[62:63], v[62:63], v[172:173] op_sel_hi:[1,0]
	v_pk_mul_f32 v[60:61], v[132:133], v[60:61]
	v_pk_mul_f32 v[62:63], v[134:135], v[62:63]
	global_store_dwordx4 v181, v[60:63], s[8:9] offset:0 nt
	v_pk_mul_f32 v[56:57], v[56:57], v[172:173] op_sel_hi:[1,0]
	v_pk_mul_f32 v[58:59], v[58:59], v[172:173] op_sel_hi:[1,0]
	v_pk_mul_f32 v[56:57], v[136:137], v[56:57]
	v_pk_mul_f32 v[58:59], v[138:139], v[58:59]
	global_store_dwordx4 v181, v[56:59], s[8:9] offset:64 nt
	v_pk_mul_f32 v[52:53], v[52:53], v[172:173] op_sel_hi:[1,0]
	v_pk_mul_f32 v[54:55], v[54:55], v[172:173] op_sel_hi:[1,0]
	v_pk_mul_f32 v[52:53], v[140:141], v[52:53]
	v_pk_mul_f32 v[54:55], v[142:143], v[54:55]
	global_store_dwordx4 v181, v[52:55], s[8:9] offset:512 nt
	v_pk_mul_f32 v[44:45], v[44:45], v[172:173] op_sel_hi:[1,0]
	v_pk_mul_f32 v[46:47], v[46:47], v[172:173] op_sel_hi:[1,0]
	v_pk_mul_f32 v[44:45], v[160:161], v[44:45]
	v_pk_mul_f32 v[46:47], v[162:163], v[46:47]
	global_store_dwordx4 v181, v[44:47], s[8:9] offset:576 nt
	v_add_u32_e32 v182, 0x120000, v180
	v_pk_mul_f32 v[48:49], v[48:49], v[174:175] op_sel_hi:[1,0]
	v_pk_mul_f32 v[50:51], v[50:51], v[174:175] op_sel_hi:[1,0]
	v_pk_mul_f32 v[48:49], v[132:133], v[48:49]
	v_pk_mul_f32 v[50:51], v[134:135], v[50:51]
	global_store_dwordx4 v182, v[48:51], s[8:9] offset:0 nt
	v_pk_mul_f32 v[40:41], v[40:41], v[174:175] op_sel_hi:[1,0]
	v_pk_mul_f32 v[42:43], v[42:43], v[174:175] op_sel_hi:[1,0]
	v_pk_mul_f32 v[40:41], v[136:137], v[40:41]
	v_pk_mul_f32 v[42:43], v[138:139], v[42:43]
	global_store_dwordx4 v182, v[40:43], s[8:9] offset:64 nt
	v_pk_mul_f32 v[36:37], v[36:37], v[174:175] op_sel_hi:[1,0]
	v_pk_mul_f32 v[38:39], v[38:39], v[174:175] op_sel_hi:[1,0]
	v_pk_mul_f32 v[36:37], v[140:141], v[36:37]
	v_pk_mul_f32 v[38:39], v[142:143], v[38:39]
	global_store_dwordx4 v182, v[36:39], s[8:9] offset:512 nt
	v_pk_mul_f32 v[28:29], v[28:29], v[174:175] op_sel_hi:[1,0]
	v_pk_mul_f32 v[30:31], v[30:31], v[174:175] op_sel_hi:[1,0]
	v_pk_mul_f32 v[28:29], v[160:161], v[28:29]
	v_pk_mul_f32 v[30:31], v[162:163], v[30:31]
	global_store_dwordx4 v182, v[28:31], s[8:9] offset:576 nt
	v_add_u32_e32 v181, 0x140000, v180
	v_pk_mul_f32 v[32:33], v[32:33], v[176:177] op_sel_hi:[1,0]
	v_pk_mul_f32 v[34:35], v[34:35], v[176:177] op_sel_hi:[1,0]
	v_pk_mul_f32 v[32:33], v[132:133], v[32:33]
	v_pk_mul_f32 v[34:35], v[134:135], v[34:35]
	global_store_dwordx4 v181, v[32:35], s[8:9] offset:0 nt
	v_pk_mul_f32 v[24:25], v[24:25], v[176:177] op_sel_hi:[1,0]
	v_pk_mul_f32 v[26:27], v[26:27], v[176:177] op_sel_hi:[1,0]
	v_pk_mul_f32 v[24:25], v[136:137], v[24:25]
	v_pk_mul_f32 v[26:27], v[138:139], v[26:27]
	global_store_dwordx4 v181, v[24:27], s[8:9] offset:64 nt
	v_pk_mul_f32 v[20:21], v[20:21], v[176:177] op_sel_hi:[1,0]
	v_pk_mul_f32 v[22:23], v[22:23], v[176:177] op_sel_hi:[1,0]
	v_pk_mul_f32 v[20:21], v[140:141], v[20:21]
	v_pk_mul_f32 v[22:23], v[142:143], v[22:23]
	global_store_dwordx4 v181, v[20:23], s[8:9] offset:512 nt
	v_pk_mul_f32 v[12:13], v[12:13], v[176:177] op_sel_hi:[1,0]
	v_pk_mul_f32 v[14:15], v[14:15], v[176:177] op_sel_hi:[1,0]
	v_pk_mul_f32 v[12:13], v[160:161], v[12:13]
	v_pk_mul_f32 v[14:15], v[162:163], v[14:15]
	global_store_dwordx4 v181, v[12:15], s[8:9] offset:576 nt
	v_add_u32_e32 v182, 0x160000, v180
	v_pk_mul_f32 v[16:17], v[16:17], v[178:179] op_sel_hi:[1,0]
	v_pk_mul_f32 v[18:19], v[18:19], v[178:179] op_sel_hi:[1,0]
	v_pk_mul_f32 v[16:17], v[132:133], v[16:17]
	v_pk_mul_f32 v[18:19], v[134:135], v[18:19]
	global_store_dwordx4 v182, v[16:19], s[8:9] offset:0 nt
	v_pk_mul_f32 v[8:9], v[8:9], v[178:179] op_sel_hi:[1,0]
	v_pk_mul_f32 v[10:11], v[10:11], v[178:179] op_sel_hi:[1,0]
	v_pk_mul_f32 v[8:9], v[136:137], v[8:9]
	v_pk_mul_f32 v[10:11], v[138:139], v[10:11]
	global_store_dwordx4 v182, v[8:11], s[8:9] offset:64 nt
	v_pk_mul_f32 v[4:5], v[4:5], v[178:179] op_sel_hi:[1,0]
	v_pk_mul_f32 v[6:7], v[6:7], v[178:179] op_sel_hi:[1,0]
	v_pk_mul_f32 v[4:5], v[140:141], v[4:5]
	v_pk_mul_f32 v[6:7], v[142:143], v[6:7]
	global_store_dwordx4 v182, v[4:7], s[8:9] offset:512 nt
	v_pk_mul_f32 v[0:1], v[0:1], v[178:179] op_sel_hi:[1,0]
	v_pk_mul_f32 v[2:3], v[2:3], v[178:179] op_sel_hi:[1,0]
	v_pk_mul_f32 v[0:1], v[160:161], v[0:1]
	v_pk_mul_f32 v[2:3], v[162:163], v[2:3]
	global_store_dwordx4 v182, v[0:3], s[8:9] offset:576 nt
	s_branch .LBB0_1668
.Lp8_nofuse:
	v_lshlrev_b32_e32 v180, 2, v148
	v_mov_b32_e32 v181, v180
	global_store_dwordx4 v181, v[124:127], s[8:9] offset:0
	global_store_dwordx4 v181, v[120:123], s[8:9] offset:64
	global_store_dwordx4 v181, v[116:119], s[8:9] offset:512
	global_store_dwordx4 v181, v[108:111], s[8:9] offset:576
	v_add_u32_e32 v182, 0x20000, v180
	global_store_dwordx4 v182, v[112:115], s[8:9] offset:0
	global_store_dwordx4 v182, v[104:107], s[8:9] offset:64
	global_store_dwordx4 v182, v[100:103], s[8:9] offset:512
	global_store_dwordx4 v182, v[92:95], s[8:9] offset:576
	v_add_u32_e32 v181, 0x40000, v180
	global_store_dwordx4 v181, v[96:99], s[8:9] offset:0
	global_store_dwordx4 v181, v[88:91], s[8:9] offset:64
	global_store_dwordx4 v181, v[84:87], s[8:9] offset:512
	global_store_dwordx4 v181, v[76:79], s[8:9] offset:576
	v_add_u32_e32 v182, 0x60000, v180
	global_store_dwordx4 v182, v[80:83], s[8:9] offset:0
	global_store_dwordx4 v182, v[72:75], s[8:9] offset:64
	global_store_dwordx4 v182, v[68:71], s[8:9] offset:512
	global_store_dwordx4 v182, v[64:67], s[8:9] offset:576
	v_add_u32_e32 v181, 0x100000, v180
	global_store_dwordx4 v181, v[60:63], s[8:9] offset:0
	global_store_dwordx4 v181, v[56:59], s[8:9] offset:64
	global_store_dwordx4 v181, v[52:55], s[8:9] offset:512
	global_store_dwordx4 v181, v[44:47], s[8:9] offset:576
	v_add_u32_e32 v182, 0x120000, v180
	global_store_dwordx4 v182, v[48:51], s[8:9] offset:0
	global_store_dwordx4 v182, v[40:43], s[8:9] offset:64
	global_store_dwordx4 v182, v[36:39], s[8:9] offset:512
	global_store_dwordx4 v182, v[28:31], s[8:9] offset:576
	v_add_u32_e32 v181, 0x140000, v180
	global_store_dwordx4 v181, v[32:35], s[8:9] offset:0
	global_store_dwordx4 v181, v[24:27], s[8:9] offset:64
	global_store_dwordx4 v181, v[20:23], s[8:9] offset:512
	global_store_dwordx4 v181, v[12:15], s[8:9] offset:576
	v_add_u32_e32 v182, 0x160000, v180
	global_store_dwordx4 v182, v[16:19], s[8:9] offset:0
	global_store_dwordx4 v182, v[8:11], s[8:9] offset:64
	global_store_dwordx4 v182, v[4:7], s[8:9] offset:512
	global_store_dwordx4 v182, v[0:3], s[8:9] offset:576
